# v22o: v21 + one static s_setprio 1 for the older wave half (waves 0-3) before the attention passes (covers pass 0/1, pooling, pass 2)
# baseline (speedup 1.0000x reference)
; __global__ void __launch_bounds__(512, 2) fwd_megakernel(Args a) {
;     ...
;         __syncthreads();
;         for (int sb = bx; sb < 768; sb += G) {
;             const int c5 = sb >> 4, sbh = sb & 15; int sseq, sS, sblk;
;             if (c5 < 16) { sseq = (c5 >> 2) * 2048; sS = 2048; sblk = c5 & 3; } else { sseq = MP; sS = 16384; sblk = c5 - 16; }
;             attn_pass<0, true>(lds, RA, RB, OACC, LACC, rel_bias, sseq, sS, sblk, sbh);
;             asm volatile("s_waitcnt vmcnt(0)" ::: "memory"); __syncthreads();
;             attn_pass<1, true>(lds, RA, RB, OACC, LACC, rel_bias, sseq, sS, sblk, sbh);
;         }
.LBB0_161:
	v_readfirstlane_b32 s0, v168
	s_nop 3
	s_lshr_b32 s0, s0, 6
	s_cmp_ge_u32 s0, 4
	s_cbranch_scc1 .Lprio_att_done
	s_setprio 1
